# speedup vs baseline: 1.0149x; 1.0149x over previous
; __device__ __forceinline__ void wkv_scan(unsigned char* ws, int scan, float* lds, int wv_) {
;     ...
;   const int ks = lane & 7, rp = wave * 8 + (lane >> 3);
;   float* yp = Y + ((size_t)(b * SEQ_ + (dir ? SEQ_ - 1 : 0))) * BW_ + h * 64 + 2 * rp;
;   const long ystep = dir ? -(long)BW_ : (long)BW_;
;   float2v S0[4], S1[4];
; #pragma unroll
;   for (int i = 0; i < 4; ++i) { S0[i] = float2v{0.f, 0.f}; S1[i] = float2v{0.f, 0.f}; }
;   __syncthreads();
;   if (wave >= 4) { pload(0); pstore(0); pload(1); }
;   __syncthreads();
.LBB0_266:
	s_or_b64 exec, exec, s[2:3]
	v_lshrrev_b32_e32 v9, 4, v6
	v_lshl_or_b32 v96, v5, 2, v9
	v_lshlrev_b32_e32 v96, 1, v96
	v_readlane_b32 s2, v252, 56
	v_mov_b32_e32 v97, 0
	v_readlane_b32 s3, v252, 57
	v_lshlrev_b32_e32 v10, 2, v4
	v_and_b32_e32 v9, 15, v6
	v_lshl_add_u64 v[98:99], v[96:97], 2, s[2:3]
	v_readlane_b32 s2, v252, 52
	v_lshlrev_b32_e32 v8, 2, v8
	v_readlane_b32 s3, v252, 53
	v_or_b32_e32 v100, s2, v4
	v_mov_b32_e32 v166, v167
	s_mov_b32 s8, 0
	v_cmp_eq_u32_e64 s[4:5], 0, v9
	v_add3_u32 v122, 0, v8, v10
	v_add_u32_e32 v123, 32, v7
	v_or_b32_e32 v101, s3, v167
	v_lshlrev_b32_e32 v112, 4, v9
	s_movk_i32 s2, 0x500
	v_lshl_add_u32 v113, v96, 2, s2
	v_readlane_b32 s14, v252, 61
	v_readlane_b32 s15, v252, 62
	v_readlane_b32 s100, v252, 59
	v_readlane_b32 s101, v252, 60
	s_nop 1
	v_lshl_add_u64 v[110:111], v[98:99], 0, s[14:15]
	v_mov_b64_e32 v[102:103], v[166:167]
	v_mov_b64_e32 v[104:105], v[166:167]
	v_mov_b64_e32 v[106:107], v[166:167]
	v_mov_b64_e32 v[108:109], v[166:167]
	s_waitcnt lgkmcnt(0)
	s_barrier
	s_branch .LBB0_268

; __device__ __forceinline__ void wkv_scan(unsigned char* ws, int scan, float* lds, int wv_) {
;     ...
;       const float* buf = lds + (c & 1) * (CH * STEPF);
;       const float* sp0 = buf + ks * 8;
;       float4 ra = *(const float4*)(sp0), rb = *(const float4*)(sp0 + 4);
;       float4 wa = *(const float4*)(sp0 + 64), wb = *(const float4*)(sp0 + 68);
;       float4 ka = *(const float4*)(sp0 + 128), kb = *(const float4*)(sp0 + 132);
;       float4 aa = *(const float4*)(sp0 + 192), ab = *(const float4*)(sp0 + 196);
;       float4 ba = *(const float4*)(sp0 + 256), bb = *(const float4*)(sp0 + 260);
;       float2 vv = *(const float2*)(buf + 320 + 2 * rp);
; #pragma unroll 2
;       for (int s = 0; s < CH; ++s) {
;         float2v r2[4] = {{ra.x, ra.y}, {ra.z, ra.w}, {rb.x, rb.y}, {rb.z, rb.w}};
;         float2v w2[4] = {{wa.x, wa.y}, {wa.z, wa.w}, {wb.x, wb.y}, {wb.z, wb.w}};
;         float2v k2[4] = {{ka.x, ka.y}, {ka.z, ka.w}, {kb.x, kb.y}, {kb.z, kb.w}};
;         float2v a2[4] = {{aa.x, aa.y}, {aa.z, aa.w}, {ab.x, ab.y}, {ab.z, ab.w}};
;         float2v b2[4] = {{ba.x, ba.y}, {ba.z, ba.w}, {bb.x, bb.y}, {bb.z, bb.w}};
;         float2v v0v = {vv.x, vv.x}, v1v = {vv.y, vv.y};
;         {
;           const int sn = (s + 1 < CH) ? (s + 1) : s;
;           const float* sp = buf + sn * STEPF + ks * 8;
;           ra = *(const float4*)(sp); rb = *(const float4*)(sp + 4);
;           wa = *(const float4*)(sp + 64); wb = *(const float4*)(sp + 68);
;           ka = *(const float4*)(sp + 128); kb = *(const float4*)(sp + 132);
;           aa = *(const float4*)(sp + 192); ab = *(const float4*)(sp + 196);
;           ba = *(const float4*)(sp + 256); bb = *(const float4*)(sp + 260);
;           vv = *(const float2*)(buf + sn * STEPF + 320 + 2 * rp);
;         }
;         float2v t0 = S0[0] * a2[0], t1 = S1[0] * a2[0];
; #pragma unroll
;         for (int i = 1; i < 4; ++i) { t0 += S0[i] * a2[i]; t1 += S1[i] * a2[i]; }
;         float sa0 = red8(t0.x + t0.y), sa1 = red8(t1.x + t1.y);
;         float2v sa0v = {sa0, sa0}, sa1v = {sa1, sa1};
; #pragma unroll
;         for (int i = 0; i < 4; ++i) {
;           S0[i] = S0[i] * w2[i] + (sa0v * b2[i] + v0v * k2[i]);
;           S1[i] = S1[i] * w2[i] + (sa1v * b2[i] + v1v * k2[i]);
;         }
;         float2v y0 = S0[0] * r2[0], y1 = S1[0] * r2[0];
; #pragma unroll
.LBB0_268:
	s_bitcmp1_b32 s8, 0
	s_cselect_b32 s6, 0x6000, 0
	v_add_u32_e32 v114, s6, v112
	v_add_u32_e32 v115, s6, v113
	ds_read_b128 v[20:23], v114 offset:768
	ds_read_b128 v[16:19], v114 offset:512
	ds_read_b64 v[28:29], v115
	ds_read_b128 v[24:27], v114 offset:1024
	ds_read_b128 v[12:15], v114 offset:256
	ds_read_b128 v[8:11], v114
	s_mov_b32 s10, 0
	s_waitcnt lgkmcnt(3)
	v_pk_mul_f32 v[34:35], v[16:17], v[28:29] op_sel_hi:[1,0]
	v_pk_mul_f32 v[36:37], v[18:19], v[28:29] op_sel_hi:[1,0]
	v_pk_mul_f32 v[38:39], v[16:17], v[28:29] op_sel:[0,1]
	v_pk_mul_f32 v[40:41], v[18:19], v[28:29] op_sel:[0,1]
.Lscan8_step:
	v_pk_mul_f32 v[30:31], v[102:103], v[20:21]
	v_pk_mul_f32 v[32:33], v[106:107], v[20:21]
	v_pk_fma_f32 v[30:31], v[104:105], v[22:23], v[30:31]
	v_pk_fma_f32 v[32:33], v[108:109], v[22:23], v[32:33]
	v_add_f32_e32 v30, v30, v31
	v_add_f32_e32 v32, v32, v33
	ds_read_b128 v[60:63], v114 offset:2304
	v_add_f32_dpp v30, v30, v30 quad_perm:[1,0,3,2] row_mask:0xf bank_mask:0xf bound_ctrl:1
	v_add_f32_dpp v32, v32, v32 quad_perm:[1,0,3,2] row_mask:0xf bank_mask:0xf bound_ctrl:1
	ds_read_b128 v[56:59], v114 offset:2048
	v_add_f32_dpp v30, v30, v30 quad_perm:[2,3,0,1] row_mask:0xf bank_mask:0xf bound_ctrl:1
	v_add_f32_dpp v32, v32, v32 quad_perm:[2,3,0,1] row_mask:0xf bank_mask:0xf bound_ctrl:1
	ds_read_b64 v[68:69], v115 offset:1536
	v_add_f32_dpp v30, v30, v30 row_half_mirror row_mask:0xf bank_mask:0xf bound_ctrl:1
	v_add_f32_dpp v32, v32, v32 row_half_mirror row_mask:0xf bank_mask:0xf bound_ctrl:1
	ds_read_b128 v[64:67], v114 offset:2560
	v_add_f32_dpp v30, v30, v30 row_mirror row_mask:0xf bank_mask:0xf bound_ctrl:1
	v_add_f32_dpp v32, v32, v32 row_mirror row_mask:0xf bank_mask:0xf bound_ctrl:1
	ds_read_b128 v[52:55], v114 offset:1792
	ds_read_b128 v[48:51], v114 offset:1536
	s_waitcnt lgkmcnt(7)
	v_pk_fma_f32 v[34:35], v[24:25], v[30:31], v[34:35] op_sel_hi:[1,0,1]
	v_pk_fma_f32 v[36:37], v[26:27], v[30:31], v[36:37] op_sel_hi:[1,0,1]
	v_pk_fma_f32 v[38:39], v[24:25], v[32:33], v[38:39] op_sel_hi:[1,0,1]
	v_pk_fma_f32 v[40:41], v[26:27], v[32:33], v[40:41] op_sel_hi:[1,0,1]
	v_pk_fma_f32 v[102:103], v[102:103], v[12:13], v[34:35]
	v_pk_fma_f32 v[104:105], v[104:105], v[14:15], v[36:37]
	v_pk_fma_f32 v[106:107], v[106:107], v[12:13], v[38:39]
	v_pk_fma_f32 v[108:109], v[108:109], v[14:15], v[40:41]
	s_waitcnt lgkmcnt(6)
	v_pk_mul_f32 v[42:43], v[102:103], v[8:9]
	v_pk_mul_f32 v[44:45], v[106:107], v[8:9]
	v_pk_fma_f32 v[42:43], v[104:105], v[10:11], v[42:43]
	v_pk_fma_f32 v[44:45], v[108:109], v[10:11], v[44:45]
	v_add_f32_e32 v42, v42, v43
	v_add_f32_e32 v43, v44, v45
	s_waitcnt lgkmcnt(3)
	v_pk_mul_f32 v[70:71], v[56:57], v[68:69] op_sel_hi:[1,0]
	v_add_f32_dpp v42, v42, v42 quad_perm:[1,0,3,2] row_mask:0xf bank_mask:0xf bound_ctrl:1
	v_add_f32_dpp v43, v43, v43 quad_perm:[1,0,3,2] row_mask:0xf bank_mask:0xf bound_ctrl:1
	v_pk_mul_f32 v[72:73], v[58:59], v[68:69] op_sel_hi:[1,0]
	v_add_f32_dpp v42, v42, v42 quad_perm:[2,3,0,1] row_mask:0xf bank_mask:0xf bound_ctrl:1
	v_add_f32_dpp v43, v43, v43 quad_perm:[2,3,0,1] row_mask:0xf bank_mask:0xf bound_ctrl:1
	v_pk_mul_f32 v[74:75], v[56:57], v[68:69] op_sel:[0,1]
	v_add_f32_dpp v42, v42, v42 row_half_mirror row_mask:0xf bank_mask:0xf bound_ctrl:1
	v_add_f32_dpp v43, v43, v43 row_half_mirror row_mask:0xf bank_mask:0xf bound_ctrl:1
	v_pk_mul_f32 v[76:77], v[58:59], v[68:69] op_sel:[0,1]
	v_add_f32_dpp v42, v42, v42 row_mirror row_mask:0xf bank_mask:0xf bound_ctrl:1
	v_add_f32_dpp v43, v43, v43 row_mirror row_mask:0xf bank_mask:0xf bound_ctrl:1
	s_and_saveexec_b64 s[6:7], s[4:5]
	global_store_dwordx2 v[98:99], v[42:43], off
	s_or_b64 exec, exec, s[6:7]
	v_pk_mul_f32 v[78:79], v[102:103], v[60:61]
	v_pk_mul_f32 v[80:81], v[106:107], v[60:61]
	v_pk_fma_f32 v[78:79], v[104:105], v[62:63], v[78:79]
	v_pk_fma_f32 v[80:81], v[108:109], v[62:63], v[80:81]
	v_add_f32_e32 v78, v78, v79
	v_add_f32_e32 v80, v80, v81
	ds_read_b128 v[20:23], v114 offset:3840
	v_add_f32_dpp v78, v78, v78 quad_perm:[1,0,3,2] row_mask:0xf bank_mask:0xf bound_ctrl:1
	v_add_f32_dpp v80, v80, v80 quad_perm:[1,0,3,2] row_mask:0xf bank_mask:0xf bound_ctrl:1
	ds_read_b128 v[16:19], v114 offset:3584
	v_add_f32_dpp v78, v78, v78 quad_perm:[2,3,0,1] row_mask:0xf bank_mask:0xf bound_ctrl:1
	v_add_f32_dpp v80, v80, v80 quad_perm:[2,3,0,1] row_mask:0xf bank_mask:0xf bound_ctrl:1
	ds_read_b64 v[28:29], v115 offset:3072
	v_add_f32_dpp v78, v78, v78 row_half_mirror row_mask:0xf bank_mask:0xf bound_ctrl:1
	v_add_f32_dpp v80, v80, v80 row_half_mirror row_mask:0xf bank_mask:0xf bound_ctrl:1
	ds_read_b128 v[24:27], v114 offset:4096
	v_add_f32_dpp v78, v78, v78 row_mirror row_mask:0xf bank_mask:0xf bound_ctrl:1
	v_add_f32_dpp v80, v80, v80 row_mirror row_mask:0xf bank_mask:0xf bound_ctrl:1
	ds_read_b128 v[12:15], v114 offset:3328
	ds_read_b128 v[8:11], v114 offset:3072
	s_waitcnt lgkmcnt(7)
	v_pk_fma_f32 v[70:71], v[64:65], v[78:79], v[70:71] op_sel_hi:[1,0,1]
	v_pk_fma_f32 v[72:73], v[66:67], v[78:79], v[72:73] op_sel_hi:[1,0,1]
	v_pk_fma_f32 v[74:75], v[64:65], v[80:81], v[74:75] op_sel_hi:[1,0,1]
	v_pk_fma_f32 v[76:77], v[66:67], v[80:81], v[76:77] op_sel_hi:[1,0,1]
	v_pk_fma_f32 v[102:103], v[102:103], v[52:53], v[70:71]
	v_pk_fma_f32 v[104:105], v[104:105], v[54:55], v[72:73]
	v_pk_fma_f32 v[106:107], v[106:107], v[52:53], v[74:75]
	v_pk_fma_f32 v[108:109], v[108:109], v[54:55], v[76:77]
	s_waitcnt lgkmcnt(6)
	v_pk_mul_f32 v[46:47], v[102:103], v[48:49]
	v_pk_mul_f32 v[82:83], v[106:107], v[48:49]
	v_pk_fma_f32 v[46:47], v[104:105], v[50:51], v[46:47]
	v_pk_fma_f32 v[82:83], v[108:109], v[50:51], v[82:83]
	v_add_f32_e32 v46, v46, v47
	v_add_f32_e32 v47, v82, v83
	s_waitcnt lgkmcnt(3)
	v_pk_mul_f32 v[34:35], v[16:17], v[28:29] op_sel_hi:[1,0]
	v_add_f32_dpp v46, v46, v46 quad_perm:[1,0,3,2] row_mask:0xf bank_mask:0xf bound_ctrl:1
	v_add_f32_dpp v47, v47, v47 quad_perm:[1,0,3,2] row_mask:0xf bank_mask:0xf bound_ctrl:1
	v_pk_mul_f32 v[36:37], v[18:19], v[28:29] op_sel_hi:[1,0]
	v_add_f32_dpp v46, v46, v46 quad_perm:[2,3,0,1] row_mask:0xf bank_mask:0xf bound_ctrl:1
	v_add_f32_dpp v47, v47, v47 quad_perm:[2,3,0,1] row_mask:0xf bank_mask:0xf bound_ctrl:1
	v_pk_mul_f32 v[38:39], v[16:17], v[28:29] op_sel:[0,1]
	v_add_f32_dpp v46, v46, v46 row_half_mirror row_mask:0xf bank_mask:0xf bound_ctrl:1
	v_add_f32_dpp v47, v47, v47 row_half_mirror row_mask:0xf bank_mask:0xf bound_ctrl:1
	v_pk_mul_f32 v[40:41], v[18:19], v[28:29] op_sel:[0,1]
	v_add_f32_dpp v46, v46, v46 row_mirror row_mask:0xf bank_mask:0xf bound_ctrl:1
	v_add_f32_dpp v47, v47, v47 row_mirror row_mask:0xf bank_mask:0xf bound_ctrl:1
	s_and_saveexec_b64 s[6:7], s[4:5]
	global_store_dwordx2 v[110:111], v[46:47], off offset:-4
	s_or_b64 exec, exec, s[6:7]
	v_add_u32_e32 v114, 0xc00, v114
	v_add_u32_e32 v115, 0xc00, v115
	v_lshl_add_u64 v[98:99], v[98:99], 0, s[100:101]
	v_lshl_add_u64 v[110:111], v[110:111], 0, s[100:101]
	s_add_i32 s10, s10, 1
	s_cmp_lg_u32 s10, 8
	s_cbranch_scc1 .Lscan8_step
; __device__ __forceinline__ void wkv_scan(unsigned char* ws, int scan, float* lds, int wv_) {
;     ...
;   auto pload = [&](int c) {
;     int si = c * CH + ps;
;     int t = dir ? (SEQ_ - 1 - si) : si;
;     size_t off = ((size_t)(b * SEQ_ + t)) * BW_ + h * 64 + pk;
;     ur = *(const uint2*)(Rr + off); uv = *(const uint2*)(Rv + off); uk = *(const uint2*)(Rk + off);
;     ukk = *(const uint2*)(Rkk + off); ua = *(const uint2*)(Ra + off); ud = *(const uint2*)(Rd + off);
;   };
;   auto pstore = [&](int c) {
;     float r4[4] = {bflo(ur.x), bfhi(ur.x), bflo(ur.y), bfhi(ur.y)};
;     float v4[4] = {bflo(uv.x), bfhi(uv.x), bflo(uv.y), bfhi(uv.y)};
;     float k4[4] = {bflo(uk.x), bfhi(uk.x), bflo(uk.y), bfhi(uk.y)};
;     float q4[4] = {bflo(ukk.x), bfhi(ukk.x), bflo(ukk.y), bfhi(ukk.y)};
;     float a4[4] = {bflo(ua.x), bfhi(ua.x), bflo(ua.y), bfhi(ua.y)};
;     float d4[4] = {bflo(ud.x), bfhi(ud.x), bflo(ud.y), bfhi(ud.y)};
;     float kav[4] = {ka4.x, ka4.y, ka4.z, ka4.w};
;     float* dst = lds + (c & 1) * (CH * STEPF) + ps * STEPF + pk;
;     float4 o;
;     o = make_float4(r4[0], r4[1], r4[2], r4[3]); *(float4*)(dst + 0) = o;
;     o = make_float4(1.f - d4[0], 1.f - d4[1], 1.f - d4[2], 1.f - d4[3]); *(float4*)(dst + 64) = o;
;     o = make_float4(k4[0] * (1.f + (a4[0] - 1.f) * kav[0]), k4[1] * (1.f + (a4[1] - 1.f) * kav[1]),
;                     k4[2] * (1.f + (a4[2] - 1.f) * kav[2]), k4[3] * (1.f + (a4[3] - 1.f) * kav[3]));
;     *(float4*)(dst + 128) = o;
;     o = make_float4(-q4[0], -q4[1], -q4[2], -q4[3]); *(float4*)(dst + 192) = o;
;     o = make_float4(q4[0] * a4[0], q4[1] * a4[1], q4[2] * a4[2], q4[3] * a4[3]); *(float4*)(dst + 256) = o;
;     o = make_float4(v4[0], v4[1], v4[2], v4[3]); *(float4*)(dst + 320) = o;
;   };
;   const int ks = lane & 7, rp = wave * 8 + (lane >> 3);
;   float* yp = Y + ((size_t)(b * SEQ_ + (dir ? SEQ_ - 1 : 0))) * BW_ + h * 64 + 2 * rp;
;   const long ystep = dir ? -(long)BW_ : (long)BW_;
;   float2v S0[4], S1[4];
; #pragma unroll
;   for (int i = 0; i < 4; ++i) { S0[i] = float2v{0.f, 0.f}; S1[i] = float2v{0.f, 0.f}; }
;   __syncthreads();
;   if (wave >= 4) { pload(0); pstore(0); pload(1); }
;   __syncthreads();
;   for (int c = 0; c < NCH; ++c) {
;     if (wave >= 4) {
;       if (c + 1 < NCH) pstore(c + 1);
;       if (c + 2 < NCH) pload(c + 2);
.LBB0_275:
	s_mov_b64 s[2:3], exec
	s_andn2_b64 exec, exec, vcc
	s_cbranch_execz .LBB0_267
	s_waitcnt lgkmcnt(0)
	s_cmpk_eq_i32 s8, 0x7f
	s_cbranch_scc1 .LBB0_278
	s_waitcnt vmcnt(12)
	s_bitcmp1_b32 s8, 0
	s_cselect_b32 s6, 0, 0x6000
	v_lshlrev_b32_e32 v4, 16, v84
	v_and_b32_e32 v5, 0xffff0000, v84
	v_lshlrev_b32_e32 v6, 16, v85
	v_and_b32_e32 v7, 0xffff0000, v85
	v_lshlrev_b32_e32 v24, 16, v92
	v_and_b32_e32 v25, 0xffff0000, v92
	v_lshlrev_b32_e32 v26, 16, v93
	v_and_b32_e32 v27, 0xffff0000, v93
	v_add_u32_e32 v28, s6, v122
	v_lshlrev_b32_e32 v20, 16, v94
	v_and_b32_e32 v21, 0xffff0000, v94
	v_lshlrev_b32_e32 v22, 16, v95
	v_and_b32_e32 v23, 0xffff0000, v95
	ds_write_b128 v28, v[4:7]
	v_pk_add_f32 v[4:5], v[24:25], 1.0 op_sel_hi:[1,0] neg_lo:[1,0] neg_hi:[1,0]
	v_pk_add_f32 v[6:7], v[26:27], 1.0 op_sel_hi:[1,0] neg_lo:[1,0] neg_hi:[1,0]
	ds_write_b128 v28, v[4:7] offset:256
	v_pk_add_f32 v[4:5], v[20:21], -1.0 op_sel_hi:[1,0]
	v_pk_add_f32 v[6:7], v[22:23], -1.0 op_sel_hi:[1,0]
	v_lshlrev_b32_e32 v12, 16, v88
	v_and_b32_e32 v13, 0xffff0000, v88
	v_lshlrev_b32_e32 v14, 16, v89
	v_and_b32_e32 v15, 0xffff0000, v89
	v_pk_fma_f32 v[4:5], v[0:1], v[4:5], 1.0 op_sel_hi:[1,1,0]
	v_pk_fma_f32 v[6:7], v[2:3], v[6:7], 1.0 op_sel_hi:[1,1,0]
	v_lshlrev_b32_e32 v16, 16, v90
	v_and_b32_e32 v17, 0xffff0000, v90
	v_lshlrev_b32_e32 v18, 16, v91
	v_and_b32_e32 v19, 0xffff0000, v91
	v_pk_mul_f32 v[4:5], v[4:5], v[12:13]
	v_pk_mul_f32 v[6:7], v[6:7], v[14:15]
	ds_write_b128 v28, v[4:7] offset:512
	v_xor_b32_e32 v5, 0x80000000, v17
	v_xor_b32_e32 v4, 0x80000000, v16
	v_xor_b32_e32 v7, 0x80000000, v19
	v_xor_b32_e32 v6, 0x80000000, v18
	ds_write_b128 v28, v[4:7] offset:768
	v_pk_mul_f32 v[4:5], v[16:17], v[20:21]
	v_pk_mul_f32 v[6:7], v[18:19], v[22:23]
	v_lshlrev_b32_e32 v8, 16, v86
	v_and_b32_e32 v9, 0xffff0000, v86
	v_lshlrev_b32_e32 v10, 16, v87
	v_and_b32_e32 v11, 0xffff0000, v87
	ds_write_b128 v28, v[4:7] offset:1024
	ds_write_b128 v28, v[8:11] offset:1280
.LBB0_278:
	s_cmpk_gt_u32 s8, 0x7d
	s_cbranch_scc1 .LBB0_267
	v_lshl_add_u32 v4, s8, 4, v123
	v_readlane_b32 s6, v251, 28
	v_sub_u32_e32 v5, 0x7ff, v4
	v_readlane_b32 s7, v251, 29
	s_nop 1
	v_cndmask_b32_e64 v4, v5, v4, s[6:7]
	v_readlane_b32 s6, v251, 27
	s_nop 1
	v_add_u32_e32 v4, s6, v4
	v_mad_i64_i32 v[4:5], s[6:7], v4, s33, v[100:101]
	v_lshlrev_b64 v[4:5], 1, v[4:5]
	v_readlane_b32 s6, v251, 21
	v_lshl_add_u64 v[6:7], s[28:29], 0, v[4:5]
	v_readlane_b32 s7, v251, 22
	v_lshl_add_u64 v[8:9], s[30:31], 0, v[4:5]
	v_lshl_add_u64 v[10:11], s[66:67], 0, v[4:5]
	v_lshl_add_u64 v[12:13], s[82:83], 0, v[4:5]
	global_load_dwordx2 v[84:85], v[6:7], off
	global_load_dwordx2 v[86:87], v[8:9], off
	global_load_dwordx2 v[88:89], v[10:11], off
	global_load_dwordx2 v[90:91], v[12:13], off
	v_lshl_add_u64 v[6:7], s[6:7], 0, v[4:5]
	v_readlane_b32 s6, v251, 25
	v_readlane_b32 s7, v251, 26
	s_nop 1
	v_lshl_add_u64 v[4:5], s[6:7], 0, v[4:5]
	global_load_dwordx2 v[94:95], v[6:7], off
	global_load_dwordx2 v[92:93], v[4:5], off
	s_branch .LBB0_267

; __global__ void __launch_bounds__(NTHREADS) fwd_megakernel(Params p) {
;   extern __shared__ __attribute__((aligned(16))) unsigned char lds[];
;   const int wv_ = __builtin_amdgcn_readfirstlane((int)(threadIdx.x >> 6));
	.amdhsa_kernel _Z14fwd_megakernel6Params
		.amdhsa_group_segment_fixed_size 0
		.amdhsa_private_segment_fixed_size 0
		.amdhsa_kernarg_size 536
		.amdhsa_user_sgpr_count 2
		.amdhsa_user_sgpr_dispatch_ptr 0
		.amdhsa_user_sgpr_queue_ptr 0
		.amdhsa_user_sgpr_kernarg_segment_ptr 1
		.amdhsa_user_sgpr_dispatch_id 0
		.amdhsa_user_sgpr_kernarg_preload_length 0
		.amdhsa_user_sgpr_kernarg_preload_offset 0
		.amdhsa_user_sgpr_private_segment_size 0
		.amdhsa_uses_dynamic_stack 0
		.amdhsa_enable_private_segment 0
		.amdhsa_system_sgpr_workgroup_id_x 1
		.amdhsa_system_sgpr_workgroup_id_y 0
		.amdhsa_system_sgpr_workgroup_id_z 0
		.amdhsa_system_sgpr_workgroup_info 0
		.amdhsa_system_vgpr_workitem_id 2
		.amdhsa_next_free_vgpr 256
		.amdhsa_next_free_sgpr 102
		.amdhsa_accum_offset 256
		.amdhsa_reserve_vcc 1
		.amdhsa_float_round_mode_32 0
		.amdhsa_float_round_mode_16_64 0
		.amdhsa_float_denorm_mode_32 3
		.amdhsa_float_denorm_mode_16_64 3
		.amdhsa_dx10_clamp 1
		.amdhsa_ieee_mode 1
		.amdhsa_fp16_overflow 0
		.amdhsa_tg_split 0
		.amdhsa_exception_fp_ieee_invalid_op 0
		.amdhsa_exception_fp_denorm_src 0
		.amdhsa_exception_fp_ieee_div_zero 0
		.amdhsa_exception_fp_ieee_overflow 0
		.amdhsa_exception_fp_ieee_underflow 0
		.amdhsa_exception_fp_ieee_inexact 0
		.amdhsa_exception_int_div_zero 0
	.end_amdhsa_kernel

; __global__ void __launch_bounds__(NTHREADS) fwd_megakernel(Params p) {
;   extern __shared__ __attribute__((aligned(16))) unsigned char lds[];
;   const int wv_ = __builtin_amdgcn_readfirstlane((int)(threadIdx.x >> 6));
amdhsa.kernels:
  - .agpr_count:     0
    .args:
      - .offset:         0
        .size:           280
        .value_kind:     by_value
      - .offset:         280
        .size:           4
        .value_kind:     hidden_block_count_x
      - .offset:         284
        .size:           4
        .value_kind:     hidden_block_count_y
      - .offset:         288
        .size:           4
        .value_kind:     hidden_block_count_z
      - .offset:         292
        .size:           2
        .value_kind:     hidden_group_size_x
      - .offset:         294
        .size:           2
        .value_kind:     hidden_group_size_y
      - .offset:         296
        .size:           2
        .value_kind:     hidden_group_size_z
      - .offset:         298
        .size:           2
        .value_kind:     hidden_remainder_x
      - .offset:         300
        .size:           2
        .value_kind:     hidden_remainder_y
      - .offset:         302
        .size:           2
        .value_kind:     hidden_remainder_z
      - .offset:         320
        .size:           8
        .value_kind:     hidden_global_offset_x
      - .offset:         328
        .size:           8
        .value_kind:     hidden_global_offset_y
      - .offset:         336
        .size:           8
        .value_kind:     hidden_global_offset_z
      - .offset:         344
        .size:           2
        .value_kind:     hidden_grid_dims
      - .offset:         368
        .size:           8
        .value_kind:     hidden_multigrid_sync_arg
      - .offset:         400
        .size:           4
        .value_kind:     hidden_dynamic_lds_size
    .group_segment_fixed_size: 0
    .kernarg_segment_align: 8
    .kernarg_segment_size: 536
    .language:       OpenCL C
    .language_version:
      - 2
      - 0
    .max_flat_workgroup_size: 512
    .name:           _Z14fwd_megakernel6Params
    .private_segment_fixed_size: 0
    .sgpr_count:     108
    .sgpr_spill_count: 342
    .symbol:         _Z14fwd_megakernel6Params.kd
    .uniform_work_group_size: 1
    .uses_dynamic_stack: false
    .vgpr_count:     256
    .vgpr_spill_count: 0
    .wavefront_size: 64
